# DSA attention QK: sel entries read up front, K-row gathers 4 blocks deep with coalescing-friendly lane mapping + ds_bpermute into MFMA layout
# speedup vs baseline: 1.0089x; 1.0089x over previous
; __device__ __forceinline__ float ozero() { float z = 0.f; asm volatile("" : "+v"(z)); return z; }
; __device__ __forceinline__ f32x4 mfma16(bf16x8 a, bf16x8 b, f32x4 c) { return __builtin_amdgcn_mfma_f32_16x16x32_bf16(a, b, c, 0, 0, 0); }
; __device__ __forceinline__ void dsa_wave(const Params& p, int rank, char* sm) {
;     ...
;     f32x4 lgA[16], lgB[16];
; #pragma unroll
;     for (int t = 0; t < 16; t++) {
;       const int slot = t * 16 + n16; const bool valid = slot < n;
;       const int key = valid ? (16383 - (int)(sel[slot] & 0x3FFFu)) : 0;
;       const bf* kp = p.KVC + (tokb + key) * 256 + 8 * kq;
;       bf16x8 a0 = *(const bf16x8*)kp, a1 = *(const bf16x8*)(kp + 32), b0 = *(const bf16x8*)(kp + 64), b1 = *(const bf16x8*)(kp + 96);
;       const float zc_ = ozero(); f32x4 ca = {zc_, zc_, zc_, zc_}, cb2 = {zc_, zc_, zc_, zc_};
;       ca = mfma16(qa[0][0], a0, ca); ca = mfma16(qa[0][1], a1, ca);
;       cb2 = mfma16(qa[1][0], b0, cb2); cb2 = mfma16(qa[1][1], b1, cb2);
;       const bool ok = valid && (kq == 0);
; #pragma unroll
;       for (int r = 0; r < 4; r++) { lgA[t][r] = ok ? ca[r] * 0.125f : -3.0e38f; lgB[t][r] = ok ? cb2[r] * 0.125f : -3.0e38f; }
;     }
.LBB0_1498:
	s_or_b64 exec, exec, s[0:1]
	v_readlane_b32 s84, v173, s79
	v_lshl_add_u32 v219, s79, 11, v172
	v_lshrrev_b32_e32 v171, 2, v202
	v_lshl_add_u32 v174, v171, 2, v219
	v_and_b32_e32 v219, 3, v202
	v_lshlrev_b32_e32 v219, 4, v219
	v_lshl_add_u32 v218, v146, 9, v219
	v_lshrrev_b32_e32 v219, 4, v202
	v_lshlrev_b32_e32 v219, 2, v219
	v_lshl_or_b32 v169, v147, 4, v219
	ds_read_b32 v194, v174
	ds_read_b32 v195, v174 offset:64
	ds_read_b32 v196, v174 offset:128
	ds_read_b32 v197, v174 offset:192
	ds_read_b32 v198, v174 offset:256
	ds_read_b32 v199, v174 offset:320
	ds_read_b32 v200, v174 offset:384
	ds_read_b32 v201, v174 offset:448
	ds_read_b32 v216, v174 offset:512
	ds_read_b32 v217, v174 offset:576
	ds_read_b32 v144, v174 offset:640
	ds_read_b32 v155, v174 offset:704
	s_waitcnt lgkmcnt(11)
	v_bitop3_b32 v194, v194, s33, v194 bitop3:0xc
	v_cmp_gt_i32_e32 vcc, s84, v171
	v_cmp_gt_i32_e64 s[0:1], s84, v147
	v_cndmask_b32_e32 v194, 0, v194, vcc
	s_and_b64 s[0:1], s[0:1], s[6:7]
	v_lshl_add_u32 v194, v194, 9, v218
	global_load_dwordx4 v[108:111], v194, s[60:61]
	global_load_dwordx4 v[32:35], v194, s[60:61] offset:128
	global_load_dwordx4 v[76:79], v194, s[60:61] offset:64
	global_load_dwordx4 v[0:3], v194, s[60:61] offset:192
	s_waitcnt lgkmcnt(10)
	s_sub_i32 s44, s84, 16
	v_bitop3_b32 v195, v195, s33, v195 bitop3:0xc
	v_cmp_gt_i32_e32 vcc, s44, v171
	v_cmp_gt_i32_e64 s[2:3], s44, v147
	v_cndmask_b32_e32 v195, 0, v195, vcc
	s_and_b64 s[2:3], s[2:3], s[6:7]
	v_lshl_add_u32 v195, v195, 9, v218
	global_load_dwordx4 v[112:115], v195, s[60:61]
	global_load_dwordx4 v[36:39], v195, s[60:61] offset:128
	global_load_dwordx4 v[80:83], v195, s[60:61] offset:64
	global_load_dwordx4 v[4:7], v195, s[60:61] offset:192
	s_waitcnt lgkmcnt(9)
	s_sub_i32 s44, s84, 32
	v_bitop3_b32 v196, v196, s33, v196 bitop3:0xc
	v_cmp_gt_i32_e32 vcc, s44, v171
	v_cmp_gt_i32_e64 s[14:15], s44, v147
	v_cndmask_b32_e32 v196, 0, v196, vcc
	s_and_b64 s[14:15], s[14:15], s[6:7]
	v_lshl_add_u32 v196, v196, 9, v218
	global_load_dwordx4 v[116:119], v196, s[60:61]
	global_load_dwordx4 v[40:43], v196, s[60:61] offset:128
	global_load_dwordx4 v[84:87], v196, s[60:61] offset:64
	global_load_dwordx4 v[8:11], v196, s[60:61] offset:192
	s_waitcnt lgkmcnt(8)
	s_sub_i32 s44, s84, 48
	v_bitop3_b32 v197, v197, s33, v197 bitop3:0xc
	v_cmp_gt_i32_e32 vcc, s44, v171
	v_cmp_gt_i32_e64 s[16:17], s44, v147
	v_cndmask_b32_e32 v197, 0, v197, vcc
	s_and_b64 s[16:17], s[16:17], s[6:7]
	v_lshl_add_u32 v197, v197, 9, v218
	global_load_dwordx4 v[120:123], v197, s[60:61]
	global_load_dwordx4 v[44:47], v197, s[60:61] offset:128
	global_load_dwordx4 v[88:91], v197, s[60:61] offset:64
	global_load_dwordx4 v[12:15], v197, s[60:61] offset:192
	ds_read_b32 v204, v174 offset:768
	ds_read_b32 v210, v174 offset:832
	ds_read_b32 v212, v174 offset:896
	ds_read_b32 v214, v174 offset:960
	s_waitcnt lgkmcnt(11)
	s_sub_i32 s44, s84, 64
	v_bitop3_b32 v198, v198, s33, v198 bitop3:0xc
	v_cmp_gt_i32_e32 vcc, s44, v171
	v_cmp_gt_i32_e64 s[18:19], s44, v147
	v_cndmask_b32_e32 v198, 0, v198, vcc
	s_and_b64 s[18:19], s[18:19], s[6:7]
	v_lshl_add_u32 v198, v198, 9, v218
	s_waitcnt lgkmcnt(10)
	s_sub_i32 s44, s84, 80
	v_bitop3_b32 v199, v199, s33, v199 bitop3:0xc
	v_cmp_gt_i32_e32 vcc, s44, v171
	v_cmp_gt_i32_e64 s[20:21], s44, v147
	v_cndmask_b32_e32 v199, 0, v199, vcc
	s_and_b64 s[20:21], s[20:21], s[6:7]
	v_lshl_add_u32 v199, v199, 9, v218
	s_waitcnt lgkmcnt(9)
	s_sub_i32 s44, s84, 96
	v_bitop3_b32 v200, v200, s33, v200 bitop3:0xc
	v_cmp_gt_i32_e32 vcc, s44, v171
	v_cmp_gt_i32_e64 s[22:23], s44, v147
	v_cndmask_b32_e32 v200, 0, v200, vcc
	s_and_b64 s[22:23], s[22:23], s[6:7]
	v_lshl_add_u32 v200, v200, 9, v218
	s_waitcnt lgkmcnt(8)
	s_sub_i32 s44, s84, 112
	v_bitop3_b32 v201, v201, s33, v201 bitop3:0xc
	v_cmp_gt_i32_e32 vcc, s44, v171
	v_cmp_gt_i32_e64 s[24:25], s44, v147
	v_cndmask_b32_e32 v201, 0, v201, vcc
	s_and_b64 s[24:25], s[24:25], s[6:7]
	v_lshl_add_u32 v201, v201, 9, v218
	s_waitcnt lgkmcnt(7)
	s_sub_i32 s44, s84, 128
	v_bitop3_b32 v216, v216, s33, v216 bitop3:0xc
	v_cmp_gt_i32_e32 vcc, s44, v171
	v_cmp_gt_i32_e64 s[26:27], s44, v147
	v_cndmask_b32_e32 v216, 0, v216, vcc
	s_and_b64 s[26:27], s[26:27], s[6:7]
	v_lshl_add_u32 v216, v216, 9, v218
	s_waitcnt lgkmcnt(6)
	s_sub_i32 s44, s84, 144
	v_bitop3_b32 v217, v217, s33, v217 bitop3:0xc
	v_cmp_gt_i32_e32 vcc, s44, v171
	v_cmp_gt_i32_e64 s[28:29], s44, v147
	v_cndmask_b32_e32 v217, 0, v217, vcc
	s_and_b64 s[28:29], s[28:29], s[6:7]
	v_lshl_add_u32 v217, v217, 9, v218
	s_waitcnt lgkmcnt(5)
	s_sub_i32 s44, s84, 160
	v_bitop3_b32 v144, v144, s33, v144 bitop3:0xc
	v_cmp_gt_i32_e32 vcc, s44, v171
	v_cmp_gt_i32_e64 s[30:31], s44, v147
	v_cndmask_b32_e32 v144, 0, v144, vcc
	s_and_b64 s[30:31], s[30:31], s[6:7]
	v_lshl_add_u32 v144, v144, 9, v218
	s_waitcnt lgkmcnt(4)
	s_sub_i32 s44, s84, 176
	v_bitop3_b32 v155, v155, s33, v155 bitop3:0xc
	v_cmp_gt_i32_e32 vcc, s44, v171
	v_cmp_gt_i32_e64 s[34:35], s44, v147
	v_cndmask_b32_e32 v155, 0, v155, vcc
	s_and_b64 s[34:35], s[34:35], s[6:7]
	v_lshl_add_u32 v155, v155, 9, v218
	s_waitcnt lgkmcnt(3)
	s_sub_i32 s44, s84, 192
	v_bitop3_b32 v204, v204, s33, v204 bitop3:0xc
	v_cmp_gt_i32_e32 vcc, s44, v171
	v_cmp_gt_i32_e64 s[36:37], s44, v147
	v_cndmask_b32_e32 v204, 0, v204, vcc
	s_and_b64 s[36:37], s[36:37], s[6:7]
	v_lshl_add_u32 v204, v204, 9, v218
	s_waitcnt lgkmcnt(2)
	s_sub_i32 s44, s84, 208
	v_bitop3_b32 v210, v210, s33, v210 bitop3:0xc
	v_cmp_gt_i32_e32 vcc, s44, v171
	v_cmp_gt_i32_e64 s[38:39], s44, v147
	v_cndmask_b32_e32 v210, 0, v210, vcc
	s_and_b64 s[38:39], s[38:39], s[6:7]
	v_lshl_add_u32 v210, v210, 9, v218
	s_waitcnt lgkmcnt(1)
; __device__ __forceinline__ float ozero() { float z = 0.f; asm volatile("" : "+v"(z)); return z; }
; __device__ __forceinline__ f32x4 mfma16(bf16x8 a, bf16x8 b, f32x4 c) { return __builtin_amdgcn_mfma_f32_16x16x32_bf16(a, b, c, 0, 0, 0); }
; __device__ __forceinline__ void dsa_wave(const Params& p, int rank, char* sm) {
;     ...
; #pragma unroll
;     for (int t = 0; t < 16; t++) {
;       const int slot = t * 16 + n16; const bool valid = slot < n;
;       const int key = valid ? (16383 - (int)(sel[slot] & 0x3FFFu)) : 0;
;       const bf* kp = p.KVC + (tokb + key) * 256 + 8 * kq;
;       bf16x8 a0 = *(const bf16x8*)kp, a1 = *(const bf16x8*)(kp + 32), b0 = *(const bf16x8*)(kp + 64), b1 = *(const bf16x8*)(kp + 96);
;       const float zc_ = ozero(); f32x4 ca = {zc_, zc_, zc_, zc_}, cb2 = {zc_, zc_, zc_, zc_};
;       ca = mfma16(qa[0][0], a0, ca); ca = mfma16(qa[0][1], a1, ca);
;       cb2 = mfma16(qa[1][0], b0, cb2); cb2 = mfma16(qa[1][1], b1, cb2);
;       const bool ok = valid && (kq == 0);
; #pragma unroll
;       for (int r = 0; r < 4; r++) { lgA[t][r] = ok ? ca[r] * 0.125f : -3.0e38f; lgB[t][r] = ok ? cb2[r] * 0.125f : -3.0e38f; }
	s_sub_i32 s44, s84, 224
	v_bitop3_b32 v212, v212, s33, v212 bitop3:0xc
	v_cmp_gt_i32_e32 vcc, s44, v171
	v_cmp_gt_i32_e64 s[40:41], s44, v147
	v_cndmask_b32_e32 v212, 0, v212, vcc
	s_and_b64 s[40:41], s[40:41], s[6:7]
	v_lshl_add_u32 v212, v212, 9, v218
	s_waitcnt lgkmcnt(0)
	s_sub_i32 s44, s84, 240
	v_bitop3_b32 v214, v214, s33, v214 bitop3:0xc
	v_cmp_gt_i32_e32 vcc, s44, v171
	v_cmp_gt_i32_e64 s[42:43], s44, v147
	v_cndmask_b32_e32 v214, 0, v214, vcc
	s_and_b64 s[42:43], s[42:43], s[6:7]
	v_lshl_add_u32 v214, v214, 9, v218
	s_waitcnt vmcnt(12)
	ds_bpermute_b32 v108, v169, v108
	ds_bpermute_b32 v109, v169, v109
	ds_bpermute_b32 v110, v169, v110
	ds_bpermute_b32 v111, v169, v111
	ds_bpermute_b32 v32, v169, v32
	ds_bpermute_b32 v33, v169, v33
	ds_bpermute_b32 v34, v169, v34
	ds_bpermute_b32 v35, v169, v35
	ds_bpermute_b32 v76, v169, v76
	ds_bpermute_b32 v77, v169, v77
	ds_bpermute_b32 v78, v169, v78
	ds_bpermute_b32 v79, v169, v79
	ds_bpermute_b32 v0, v169, v0
	ds_bpermute_b32 v1, v169, v1
	ds_bpermute_b32 v2, v169, v2
	ds_bpermute_b32 v3, v169, v3
	s_waitcnt lgkmcnt(0)
	v_mfma_f32_16x16x32_bf16 v[108:111], v[60:63], v[108:111], 0
	v_mfma_f32_16x16x32_bf16 v[32:35], v[68:71], v[32:35], 0
	v_mfma_f32_16x16x32_bf16 v[76:79], v[64:67], v[76:79], v[108:111]
	v_mfma_f32_16x16x32_bf16 v[0:3], v[72:75], v[0:3], v[32:35]
	s_nop 7
	global_load_dwordx4 v[124:127], v198, s[60:61]
	global_load_dwordx4 v[48:51], v198, s[60:61] offset:128
	global_load_dwordx4 v[92:95], v198, s[60:61] offset:64
	global_load_dwordx4 v[16:19], v198, s[60:61] offset:192
	s_waitcnt vmcnt(12)
	ds_bpermute_b32 v112, v169, v112
	ds_bpermute_b32 v113, v169, v113
	ds_bpermute_b32 v114, v169, v114
	ds_bpermute_b32 v115, v169, v115
	ds_bpermute_b32 v36, v169, v36
	ds_bpermute_b32 v37, v169, v37
	ds_bpermute_b32 v38, v169, v38
	ds_bpermute_b32 v39, v169, v39
	ds_bpermute_b32 v80, v169, v80
	ds_bpermute_b32 v81, v169, v81
	ds_bpermute_b32 v82, v169, v82
	ds_bpermute_b32 v83, v169, v83
	ds_bpermute_b32 v4, v169, v4
	ds_bpermute_b32 v5, v169, v5
	ds_bpermute_b32 v6, v169, v6
	ds_bpermute_b32 v7, v169, v7
	s_waitcnt lgkmcnt(0)
	v_mfma_f32_16x16x32_bf16 v[112:115], v[60:63], v[112:115], 0
	v_mfma_f32_16x16x32_bf16 v[36:39], v[68:71], v[36:39], 0
	v_mfma_f32_16x16x32_bf16 v[80:83], v[64:67], v[80:83], v[112:115]
	v_mfma_f32_16x16x32_bf16 v[4:7], v[72:75], v[4:7], v[36:39]
	s_nop 7
	global_load_dwordx4 v[128:131], v199, s[60:61]
	global_load_dwordx4 v[52:55], v199, s[60:61] offset:128
	global_load_dwordx4 v[96:99], v199, s[60:61] offset:64
	global_load_dwordx4 v[20:23], v199, s[60:61] offset:192
	s_waitcnt vmcnt(12)
	ds_bpermute_b32 v116, v169, v116
	ds_bpermute_b32 v117, v169, v117
	ds_bpermute_b32 v118, v169, v118
	ds_bpermute_b32 v119, v169, v119
	ds_bpermute_b32 v40, v169, v40
	ds_bpermute_b32 v41, v169, v41
	ds_bpermute_b32 v42, v169, v42
	ds_bpermute_b32 v43, v169, v43
	ds_bpermute_b32 v84, v169, v84
	ds_bpermute_b32 v85, v169, v85
	ds_bpermute_b32 v86, v169, v86
	ds_bpermute_b32 v87, v169, v87
	ds_bpermute_b32 v8, v169, v8
	ds_bpermute_b32 v9, v169, v9
	ds_bpermute_b32 v10, v169, v10
	ds_bpermute_b32 v11, v169, v11
	s_waitcnt lgkmcnt(0)
	v_mfma_f32_16x16x32_bf16 v[116:119], v[60:63], v[116:119], 0
	v_mfma_f32_16x16x32_bf16 v[40:43], v[68:71], v[40:43], 0
	v_mfma_f32_16x16x32_bf16 v[84:87], v[64:67], v[84:87], v[116:119]
	v_mfma_f32_16x16x32_bf16 v[8:11], v[72:75], v[8:11], v[40:43]
	s_nop 7
	global_load_dwordx4 v[132:135], v200, s[60:61]
	global_load_dwordx4 v[56:59], v200, s[60:61] offset:128
	global_load_dwordx4 v[100:103], v200, s[60:61] offset:64
	global_load_dwordx4 v[24:27], v200, s[60:61] offset:192
	s_waitcnt vmcnt(12)
	ds_bpermute_b32 v120, v169, v120
	ds_bpermute_b32 v121, v169, v121
	ds_bpermute_b32 v122, v169, v122
	ds_bpermute_b32 v123, v169, v123
	ds_bpermute_b32 v44, v169, v44
	ds_bpermute_b32 v45, v169, v45
	ds_bpermute_b32 v46, v169, v46
	ds_bpermute_b32 v47, v169, v47
	ds_bpermute_b32 v88, v169, v88
	ds_bpermute_b32 v89, v169, v89
	ds_bpermute_b32 v90, v169, v90
	ds_bpermute_b32 v91, v169, v91
	ds_bpermute_b32 v12, v169, v12
	ds_bpermute_b32 v13, v169, v13
	ds_bpermute_b32 v14, v169, v14
	ds_bpermute_b32 v15, v169, v15
	s_waitcnt lgkmcnt(0)
	v_mfma_f32_16x16x32_bf16 v[120:123], v[60:63], v[120:123], 0
	v_mfma_f32_16x16x32_bf16 v[44:47], v[68:71], v[44:47], 0
	v_mfma_f32_16x16x32_bf16 v[88:91], v[64:67], v[88:91], v[120:123]
	v_mfma_f32_16x16x32_bf16 v[12:15], v[72:75], v[12:15], v[44:47]
	s_nop 7
	global_load_dwordx4 v[164:167], v201, s[60:61]
	global_load_dwordx4 v[190:193], v201, s[60:61] offset:128
	global_load_dwordx4 v[104:107], v201, s[60:61] offset:64
	global_load_dwordx4 v[28:31], v201, s[60:61] offset:192
	s_waitcnt vmcnt(12)
	ds_bpermute_b32 v124, v169, v124
	ds_bpermute_b32 v125, v169, v125
	ds_bpermute_b32 v126, v169, v126
	ds_bpermute_b32 v127, v169, v127
	ds_bpermute_b32 v48, v169, v48
	ds_bpermute_b32 v49, v169, v49
	ds_bpermute_b32 v50, v169, v50
	ds_bpermute_b32 v51, v169, v51
	ds_bpermute_b32 v92, v169, v92
	ds_bpermute_b32 v93, v169, v93
	ds_bpermute_b32 v94, v169, v94
	ds_bpermute_b32 v95, v169, v95
	ds_bpermute_b32 v16, v169, v16
	ds_bpermute_b32 v17, v169, v17
	ds_bpermute_b32 v18, v169, v18
	ds_bpermute_b32 v19, v169, v19
	s_waitcnt lgkmcnt(0)
	v_mfma_f32_16x16x32_bf16 v[124:127], v[60:63], v[124:127], 0
	v_mfma_f32_16x16x32_bf16 v[48:51], v[68:71], v[48:51], 0
	v_mfma_f32_16x16x32_bf16 v[92:95], v[64:67], v[92:95], v[124:127]
	v_mfma_f32_16x16x32_bf16 v[16:19], v[72:75], v[16:19], v[48:51]
	s_nop 7
	global_load_dwordx4 v[156:159], v216, s[60:61]
	global_load_dwordx4 v[160:163], v216, s[60:61] offset:128
	global_load_dwordx4 v[108:111], v216, s[60:61] offset:64
	global_load_dwordx4 v[32:35], v216, s[60:61] offset:192
	s_waitcnt vmcnt(12)
; __device__ __forceinline__ float ozero() { float z = 0.f; asm volatile("" : "+v"(z)); return z; }
; __device__ __forceinline__ f32x4 mfma16(bf16x8 a, bf16x8 b, f32x4 c) { return __builtin_amdgcn_mfma_f32_16x16x32_bf16(a, b, c, 0, 0, 0); }
; __device__ __forceinline__ void dsa_wave(const Params& p, int rank, char* sm) {
;     ...
; #pragma unroll
;     for (int t = 0; t < 16; t++) {
;       const int slot = t * 16 + n16; const bool valid = slot < n;
;       const int key = valid ? (16383 - (int)(sel[slot] & 0x3FFFu)) : 0;
;       const bf* kp = p.KVC + (tokb + key) * 256 + 8 * kq;
;       bf16x8 a0 = *(const bf16x8*)kp, a1 = *(const bf16x8*)(kp + 32), b0 = *(const bf16x8*)(kp + 64), b1 = *(const bf16x8*)(kp + 96);
;       const float zc_ = ozero(); f32x4 ca = {zc_, zc_, zc_, zc_}, cb2 = {zc_, zc_, zc_, zc_};
;       ca = mfma16(qa[0][0], a0, ca); ca = mfma16(qa[0][1], a1, ca);
;       cb2 = mfma16(qa[1][0], b0, cb2); cb2 = mfma16(qa[1][1], b1, cb2);
;       const bool ok = valid && (kq == 0);
; #pragma unroll
;       for (int r = 0; r < 4; r++) { lgA[t][r] = ok ? ca[r] * 0.125f : -3.0e38f; lgB[t][r] = ok ? cb2[r] * 0.125f : -3.0e38f; }
	ds_bpermute_b32 v128, v169, v128
	ds_bpermute_b32 v129, v169, v129
	ds_bpermute_b32 v130, v169, v130
	ds_bpermute_b32 v131, v169, v131
	ds_bpermute_b32 v52, v169, v52
	ds_bpermute_b32 v53, v169, v53
	ds_bpermute_b32 v54, v169, v54
	ds_bpermute_b32 v55, v169, v55
	ds_bpermute_b32 v96, v169, v96
	ds_bpermute_b32 v97, v169, v97
	ds_bpermute_b32 v98, v169, v98
	ds_bpermute_b32 v99, v169, v99
	ds_bpermute_b32 v20, v169, v20
	ds_bpermute_b32 v21, v169, v21
	ds_bpermute_b32 v22, v169, v22
	ds_bpermute_b32 v23, v169, v23
	s_waitcnt lgkmcnt(0)
	v_mfma_f32_16x16x32_bf16 v[128:131], v[60:63], v[128:131], 0
	v_mfma_f32_16x16x32_bf16 v[52:55], v[68:71], v[52:55], 0
	v_mfma_f32_16x16x32_bf16 v[96:99], v[64:67], v[96:99], v[128:131]
	v_mfma_f32_16x16x32_bf16 v[20:23], v[72:75], v[20:23], v[52:55]
	s_nop 7
	global_load_dwordx4 v[194:197], v217, s[60:61]
	global_load_dwordx4 v[198:201], v217, s[60:61] offset:128
	global_load_dwordx4 v[112:115], v217, s[60:61] offset:64
	global_load_dwordx4 v[36:39], v217, s[60:61] offset:192
	s_waitcnt vmcnt(12)
	ds_bpermute_b32 v132, v169, v132
	ds_bpermute_b32 v133, v169, v133
	ds_bpermute_b32 v134, v169, v134
	ds_bpermute_b32 v135, v169, v135
	ds_bpermute_b32 v56, v169, v56
	ds_bpermute_b32 v57, v169, v57
	ds_bpermute_b32 v58, v169, v58
	ds_bpermute_b32 v59, v169, v59
	ds_bpermute_b32 v100, v169, v100
	ds_bpermute_b32 v101, v169, v101
	ds_bpermute_b32 v102, v169, v102
	ds_bpermute_b32 v103, v169, v103
	ds_bpermute_b32 v24, v169, v24
	ds_bpermute_b32 v25, v169, v25
	ds_bpermute_b32 v26, v169, v26
	ds_bpermute_b32 v27, v169, v27
	s_waitcnt lgkmcnt(0)
	v_mfma_f32_16x16x32_bf16 v[132:135], v[60:63], v[132:135], 0
	v_mfma_f32_16x16x32_bf16 v[56:59], v[68:71], v[56:59], 0
	v_mfma_f32_16x16x32_bf16 v[100:103], v[64:67], v[100:103], v[132:135]
	v_mfma_f32_16x16x32_bf16 v[24:27], v[72:75], v[24:27], v[56:59]
	s_nop 7
	global_load_dwordx4 v[216:219], v144, s[60:61]
	global_load_dwordx4 v[220:223], v144, s[60:61] offset:128
	global_load_dwordx4 v[116:119], v144, s[60:61] offset:64
	global_load_dwordx4 v[40:43], v144, s[60:61] offset:192
	s_waitcnt vmcnt(12)
	ds_bpermute_b32 v164, v169, v164
	ds_bpermute_b32 v165, v169, v165
	ds_bpermute_b32 v166, v169, v166
	ds_bpermute_b32 v167, v169, v167
	ds_bpermute_b32 v190, v169, v190
	ds_bpermute_b32 v191, v169, v191
	ds_bpermute_b32 v192, v169, v192
	ds_bpermute_b32 v193, v169, v193
	ds_bpermute_b32 v104, v169, v104
	ds_bpermute_b32 v105, v169, v105
	ds_bpermute_b32 v106, v169, v106
	ds_bpermute_b32 v107, v169, v107
	ds_bpermute_b32 v28, v169, v28
	ds_bpermute_b32 v29, v169, v29
	ds_bpermute_b32 v30, v169, v30
	ds_bpermute_b32 v31, v169, v31
	s_waitcnt lgkmcnt(0)
	v_mfma_f32_16x16x32_bf16 v[164:167], v[60:63], v[164:167], 0
	v_mfma_f32_16x16x32_bf16 v[190:193], v[68:71], v[190:193], 0
	v_mfma_f32_16x16x32_bf16 v[104:107], v[64:67], v[104:107], v[164:167]
	v_mfma_f32_16x16x32_bf16 v[28:31], v[72:75], v[28:31], v[190:193]
	s_nop 7
	global_load_dwordx4 v[164:167], v155, s[60:61]
	global_load_dwordx4 v[190:193], v155, s[60:61] offset:128
	global_load_dwordx4 v[120:123], v155, s[60:61] offset:64
	global_load_dwordx4 v[44:47], v155, s[60:61] offset:192
	s_waitcnt vmcnt(12)
	ds_bpermute_b32 v156, v169, v156
	ds_bpermute_b32 v157, v169, v157
	ds_bpermute_b32 v158, v169, v158
	ds_bpermute_b32 v159, v169, v159
	ds_bpermute_b32 v160, v169, v160
	ds_bpermute_b32 v161, v169, v161
	ds_bpermute_b32 v162, v169, v162
	ds_bpermute_b32 v163, v169, v163
	ds_bpermute_b32 v108, v169, v108
	ds_bpermute_b32 v109, v169, v109
	ds_bpermute_b32 v110, v169, v110
	ds_bpermute_b32 v111, v169, v111
	ds_bpermute_b32 v32, v169, v32
	ds_bpermute_b32 v33, v169, v33
	ds_bpermute_b32 v34, v169, v34
	ds_bpermute_b32 v35, v169, v35
	s_waitcnt lgkmcnt(0)
	v_mfma_f32_16x16x32_bf16 v[156:159], v[60:63], v[156:159], 0
	v_mfma_f32_16x16x32_bf16 v[160:163], v[68:71], v[160:163], 0
	v_mfma_f32_16x16x32_bf16 v[108:111], v[64:67], v[108:111], v[156:159]
	v_mfma_f32_16x16x32_bf16 v[32:35], v[72:75], v[32:35], v[160:163]
	s_nop 7
	global_load_dwordx4 v[156:159], v204, s[60:61]
	global_load_dwordx4 v[160:163], v204, s[60:61] offset:128
	global_load_dwordx4 v[124:127], v204, s[60:61] offset:64
	global_load_dwordx4 v[48:51], v204, s[60:61] offset:192
	s_waitcnt vmcnt(12)
	ds_bpermute_b32 v194, v169, v194
	ds_bpermute_b32 v195, v169, v195
	ds_bpermute_b32 v196, v169, v196
	ds_bpermute_b32 v197, v169, v197
	ds_bpermute_b32 v198, v169, v198
	ds_bpermute_b32 v199, v169, v199
	ds_bpermute_b32 v200, v169, v200
	ds_bpermute_b32 v201, v169, v201
	ds_bpermute_b32 v112, v169, v112
	ds_bpermute_b32 v113, v169, v113
	ds_bpermute_b32 v114, v169, v114
	ds_bpermute_b32 v115, v169, v115
	ds_bpermute_b32 v36, v169, v36
	ds_bpermute_b32 v37, v169, v37
	ds_bpermute_b32 v38, v169, v38
	ds_bpermute_b32 v39, v169, v39
	s_waitcnt lgkmcnt(0)
	v_mfma_f32_16x16x32_bf16 v[194:197], v[60:63], v[194:197], 0
	v_mfma_f32_16x16x32_bf16 v[198:201], v[68:71], v[198:201], 0
	v_mfma_f32_16x16x32_bf16 v[112:115], v[64:67], v[112:115], v[194:197]
	v_mfma_f32_16x16x32_bf16 v[36:39], v[72:75], v[36:39], v[198:201]
	s_nop 7
	global_load_dwordx4 v[194:197], v210, s[60:61]
	global_load_dwordx4 v[198:201], v210, s[60:61] offset:128
	global_load_dwordx4 v[128:131], v210, s[60:61] offset:64
	global_load_dwordx4 v[52:55], v210, s[60:61] offset:192
	s_waitcnt vmcnt(12)
	ds_bpermute_b32 v216, v169, v216
	ds_bpermute_b32 v217, v169, v217
	ds_bpermute_b32 v218, v169, v218
	ds_bpermute_b32 v219, v169, v219
	ds_bpermute_b32 v220, v169, v220
	ds_bpermute_b32 v221, v169, v221
	ds_bpermute_b32 v222, v169, v222
	ds_bpermute_b32 v223, v169, v223
	ds_bpermute_b32 v116, v169, v116
	ds_bpermute_b32 v117, v169, v117
	ds_bpermute_b32 v118, v169, v118
	ds_bpermute_b32 v119, v169, v119
	ds_bpermute_b32 v40, v169, v40
	ds_bpermute_b32 v41, v169, v41
	ds_bpermute_b32 v42, v169, v42
	ds_bpermute_b32 v43, v169, v43
	s_waitcnt lgkmcnt(0)
; __device__ __forceinline__ float ozero() { float z = 0.f; asm volatile("" : "+v"(z)); return z; }
; __device__ __forceinline__ f32x4 mfma16(bf16x8 a, bf16x8 b, f32x4 c) { return __builtin_amdgcn_mfma_f32_16x16x32_bf16(a, b, c, 0, 0, 0); }
; __device__ __forceinline__ void dsa_wave(const Params& p, int rank, char* sm) {
;     ...
; #pragma unroll
;     for (int t = 0; t < 16; t++) {
;       const int slot = t * 16 + n16; const bool valid = slot < n;
;       const int key = valid ? (16383 - (int)(sel[slot] & 0x3FFFu)) : 0;
;       const bf* kp = p.KVC + (tokb + key) * 256 + 8 * kq;
;       bf16x8 a0 = *(const bf16x8*)kp, a1 = *(const bf16x8*)(kp + 32), b0 = *(const bf16x8*)(kp + 64), b1 = *(const bf16x8*)(kp + 96);
;       const float zc_ = ozero(); f32x4 ca = {zc_, zc_, zc_, zc_}, cb2 = {zc_, zc_, zc_, zc_};
;       ca = mfma16(qa[0][0], a0, ca); ca = mfma16(qa[0][1], a1, ca);
;       cb2 = mfma16(qa[1][0], b0, cb2); cb2 = mfma16(qa[1][1], b1, cb2);
;       const bool ok = valid && (kq == 0);
; #pragma unroll
;       for (int r = 0; r < 4; r++) { lgA[t][r] = ok ? ca[r] * 0.125f : -3.0e38f; lgB[t][r] = ok ? cb2[r] * 0.125f : -3.0e38f; }
	v_mfma_f32_16x16x32_bf16 v[216:219], v[60:63], v[216:219], 0
	v_mfma_f32_16x16x32_bf16 v[220:223], v[68:71], v[220:223], 0
	v_mfma_f32_16x16x32_bf16 v[116:119], v[64:67], v[116:119], v[216:219]
	v_mfma_f32_16x16x32_bf16 v[40:43], v[72:75], v[40:43], v[220:223]
	s_nop 7
	global_load_dwordx4 v[216:219], v212, s[60:61]
	global_load_dwordx4 v[220:223], v212, s[60:61] offset:128
	global_load_dwordx4 v[132:135], v212, s[60:61] offset:64
	global_load_dwordx4 v[56:59], v212, s[60:61] offset:192
	s_waitcnt vmcnt(12)
	ds_bpermute_b32 v164, v169, v164
	ds_bpermute_b32 v165, v169, v165
	ds_bpermute_b32 v166, v169, v166
	ds_bpermute_b32 v167, v169, v167
	ds_bpermute_b32 v190, v169, v190
	ds_bpermute_b32 v191, v169, v191
	ds_bpermute_b32 v192, v169, v192
	ds_bpermute_b32 v193, v169, v193
	ds_bpermute_b32 v120, v169, v120
	ds_bpermute_b32 v121, v169, v121
	ds_bpermute_b32 v122, v169, v122
	ds_bpermute_b32 v123, v169, v123
	ds_bpermute_b32 v44, v169, v44
	ds_bpermute_b32 v45, v169, v45
	ds_bpermute_b32 v46, v169, v46
	ds_bpermute_b32 v47, v169, v47
	s_waitcnt lgkmcnt(0)
	v_mfma_f32_16x16x32_bf16 v[164:167], v[60:63], v[164:167], 0
	v_mfma_f32_16x16x32_bf16 v[190:193], v[68:71], v[190:193], 0
	v_mfma_f32_16x16x32_bf16 v[120:123], v[64:67], v[120:123], v[164:167]
	v_mfma_f32_16x16x32_bf16 v[44:47], v[72:75], v[44:47], v[190:193]
	s_nop 7
	s_waitcnt vmcnt(8)
	ds_bpermute_b32 v156, v169, v156
	ds_bpermute_b32 v157, v169, v157
	ds_bpermute_b32 v158, v169, v158
	ds_bpermute_b32 v159, v169, v159
	ds_bpermute_b32 v160, v169, v160
	ds_bpermute_b32 v161, v169, v161
	ds_bpermute_b32 v162, v169, v162
	ds_bpermute_b32 v163, v169, v163
	ds_bpermute_b32 v124, v169, v124
	ds_bpermute_b32 v125, v169, v125
	ds_bpermute_b32 v126, v169, v126
	ds_bpermute_b32 v127, v169, v127
	ds_bpermute_b32 v48, v169, v48
	ds_bpermute_b32 v49, v169, v49
	ds_bpermute_b32 v50, v169, v50
	ds_bpermute_b32 v51, v169, v51
	s_waitcnt lgkmcnt(0)
	v_mfma_f32_16x16x32_bf16 v[156:159], v[60:63], v[156:159], 0
	v_mfma_f32_16x16x32_bf16 v[160:163], v[68:71], v[160:163], 0
	v_mfma_f32_16x16x32_bf16 v[124:127], v[64:67], v[124:127], v[156:159]
	v_mfma_f32_16x16x32_bf16 v[48:51], v[72:75], v[48:51], v[160:163]
	s_nop 7
	global_load_dwordx4 v[156:159], v214, s[60:61]
	global_load_dwordx4 v[160:163], v214, s[60:61] offset:64
	global_load_dwordx4 v[164:167], v214, s[60:61] offset:128
	global_load_dwordx4 v[190:193], v214, s[60:61] offset:192
	s_waitcnt vmcnt(8)
	ds_bpermute_b32 v194, v169, v194
	ds_bpermute_b32 v195, v169, v195
	ds_bpermute_b32 v196, v169, v196
	ds_bpermute_b32 v197, v169, v197
	ds_bpermute_b32 v198, v169, v198
	ds_bpermute_b32 v199, v169, v199
	ds_bpermute_b32 v200, v169, v200
	ds_bpermute_b32 v201, v169, v201
	ds_bpermute_b32 v128, v169, v128
	ds_bpermute_b32 v129, v169, v129
	ds_bpermute_b32 v130, v169, v130
	ds_bpermute_b32 v131, v169, v131
	ds_bpermute_b32 v52, v169, v52
	ds_bpermute_b32 v53, v169, v53
	ds_bpermute_b32 v54, v169, v54
	ds_bpermute_b32 v55, v169, v55
	s_waitcnt lgkmcnt(0)
	v_mfma_f32_16x16x32_bf16 v[194:197], v[60:63], v[194:197], 0
	v_mfma_f32_16x16x32_bf16 v[198:201], v[68:71], v[198:201], 0
	v_mfma_f32_16x16x32_bf16 v[128:131], v[64:67], v[128:131], v[194:197]
	v_mfma_f32_16x16x32_bf16 v[52:55], v[72:75], v[52:55], v[198:201]
	s_nop 7
	s_waitcnt vmcnt(4)
	ds_bpermute_b32 v216, v169, v216
	ds_bpermute_b32 v217, v169, v217
	ds_bpermute_b32 v218, v169, v218
	ds_bpermute_b32 v219, v169, v219
	ds_bpermute_b32 v220, v169, v220
	ds_bpermute_b32 v221, v169, v221
	ds_bpermute_b32 v222, v169, v222
	ds_bpermute_b32 v223, v169, v223
	ds_bpermute_b32 v132, v169, v132
	ds_bpermute_b32 v133, v169, v133
	ds_bpermute_b32 v134, v169, v134
	ds_bpermute_b32 v135, v169, v135
	ds_bpermute_b32 v56, v169, v56
	ds_bpermute_b32 v57, v169, v57
	ds_bpermute_b32 v58, v169, v58
	ds_bpermute_b32 v59, v169, v59
	s_waitcnt lgkmcnt(0)
	v_mfma_f32_16x16x32_bf16 v[216:219], v[60:63], v[216:219], 0
	v_mfma_f32_16x16x32_bf16 v[220:223], v[68:71], v[220:223], 0
	v_mfma_f32_16x16x32_bf16 v[132:135], v[64:67], v[132:135], v[216:219]
	v_mfma_f32_16x16x32_bf16 v[56:59], v[72:75], v[56:59], v[220:223]
	s_nop 7
	s_nop 3
	s_nop 2
	v_mul_f32_e32 v132, 0x3e000000, v132
	v_cndmask_b32_e64 v198, v209, v132, s[40:41]
	v_mul_f32_e32 v132, 0x3e000000, v133
	v_cndmask_b32_e64 v155, v209, v132, s[40:41]
	v_mul_f32_e32 v132, 0x3e000000, v134
	v_mul_f32_e32 v128, 0x3e000000, v128
	v_cndmask_b32_e64 v133, v209, v132, s[40:41]
	v_mul_f32_e32 v132, 0x3e000000, v135
	v_cndmask_b32_e64 v135, v209, v128, s[38:39]
	v_mul_f32_e32 v128, 0x3e000000, v129
	v_cndmask_b32_e64 v134, v209, v128, s[38:39]
	v_mul_f32_e32 v128, 0x3e000000, v130
	v_mul_f32_e32 v124, 0x3e000000, v124
	v_cndmask_b32_e64 v129, v209, v128, s[38:39]
	v_mul_f32_e32 v128, 0x3e000000, v131
	v_cndmask_b32_e64 v131, v209, v124, s[36:37]
	v_mul_f32_e32 v124, 0x3e000000, v125
	v_cndmask_b32_e64 v130, v209, v124, s[36:37]
	v_mul_f32_e32 v124, 0x3e000000, v126
	v_mul_f32_e32 v120, 0x3e000000, v120
	v_cndmask_b32_e64 v125, v209, v124, s[36:37]
	v_mul_f32_e32 v124, 0x3e000000, v127
	v_cndmask_b32_e64 v127, v209, v120, s[34:35]
	v_mul_f32_e32 v120, 0x3e000000, v121
	v_cndmask_b32_e64 v126, v209, v120, s[34:35]
	v_mul_f32_e32 v120, 0x3e000000, v122
	v_mul_f32_e32 v116, 0x3e000000, v116
	v_cndmask_b32_e64 v121, v209, v120, s[34:35]
	v_mul_f32_e32 v120, 0x3e000000, v123
	v_cndmask_b32_e64 v123, v209, v116, s[30:31]
	v_mul_f32_e32 v116, 0x3e000000, v117
	v_cndmask_b32_e64 v122, v209, v116, s[30:31]
	v_mul_f32_e32 v116, 0x3e000000, v118
	v_cndmask_b32_e64 v117, v209, v116, s[30:31]
	v_mul_f32_e32 v116, 0x3e000000, v119
	v_mov_b32_e32 v194, v145
	v_mul_f32_e32 v112, 0x3e000000, v112
; __device__ __forceinline__ f32x4 mfma16(bf16x8 a, bf16x8 b, f32x4 c) { return __builtin_amdgcn_mfma_f32_16x16x32_bf16(a, b, c, 0, 0, 0); }
; __device__ __forceinline__ void dsa_wave(const Params& p, int rank, char* sm) {
;     ...
;       ca = mfma16(qa[0][0], a0, ca); ca = mfma16(qa[0][1], a1, ca);
;       cb2 = mfma16(qa[1][0], b0, cb2); cb2 = mfma16(qa[1][1], b1, cb2);
;       const bool ok = valid && (kq == 0);
; #pragma unroll
;       for (int r = 0; r < 4; r++) { lgA[t][r] = ok ? ca[r] * 0.125f : -3.0e38f; lgB[t][r] = ok ? cb2[r] * 0.125f : -3.0e38f; }
;     }
;     __builtin_amdgcn_wave_barrier();
	v_mov_b32_e32 v195, v194
	v_mov_b32_e32 v196, v194
	v_mov_b32_e32 v197, v194
	v_cndmask_b32_e64 v144, v209, v112, s[28:29]
	v_mul_f32_e32 v112, 0x3e000000, v113
	v_mul_f32_e32 v108, 0x3e000000, v108
	v_cndmask_b32_e64 v154, v209, v112, s[28:29]
	v_mul_f32_e32 v112, 0x3e000000, v114
	v_cndmask_b32_e64 v114, v209, v108, s[26:27]
	v_mul_f32_e32 v108, 0x3e000000, v109
	v_mul_f32_e32 v104, 0x3e000000, v104
	v_cndmask_b32_e64 v113, v209, v112, s[28:29]
	v_mul_f32_e32 v112, 0x3e000000, v115
	v_cndmask_b32_e64 v115, v209, v108, s[26:27]
	v_mul_f32_e32 v108, 0x3e000000, v110
	v_cndmask_b32_e64 v110, v209, v104, s[24:25]
	v_mul_f32_e32 v104, 0x3e000000, v105
	v_mul_f32_e32 v100, 0x3e000000, v100
	v_cndmask_b32_e64 v109, v209, v108, s[26:27]
	v_mul_f32_e32 v108, 0x3e000000, v111
	v_cndmask_b32_e64 v111, v209, v104, s[24:25]
	v_mul_f32_e32 v104, 0x3e000000, v106
	v_cndmask_b32_e64 v106, v209, v100, s[22:23]
	v_mul_f32_e32 v100, 0x3e000000, v101
	v_mul_f32_e32 v96, 0x3e000000, v96
	v_cndmask_b32_e64 v101, v209, v100, s[22:23]
	v_mul_f32_e32 v100, 0x3e000000, v102
	v_cndmask_b32_e64 v102, v209, v96, s[20:21]
	v_mul_f32_e32 v96, 0x3e000000, v97
	v_mul_f32_e32 v92, 0x3e000000, v92
	v_cndmask_b32_e64 v97, v209, v96, s[20:21]
	v_mul_f32_e32 v96, 0x3e000000, v98
	v_cndmask_b32_e64 v98, v209, v92, s[18:19]
	v_mul_f32_e32 v92, 0x3e000000, v93
	v_mul_f32_e32 v88, 0x3e000000, v88
	v_cndmask_b32_e64 v93, v209, v92, s[18:19]
	v_mul_f32_e32 v92, 0x3e000000, v94
	v_cndmask_b32_e64 v94, v209, v88, s[16:17]
	v_mul_f32_e32 v88, 0x3e000000, v89
	v_mul_f32_e32 v84, 0x3e000000, v84
	v_mul_f32_e32 v80, 0x3e000000, v80
	v_mul_f32_e32 v76, 0x3e000000, v76
	v_cndmask_b32_e64 v89, v209, v88, s[16:17]
	v_mul_f32_e32 v88, 0x3e000000, v90
	v_cndmask_b32_e64 v90, v209, v84, s[14:15]
	v_mul_f32_e32 v84, 0x3e000000, v85
	v_cndmask_b32_e64 v85, v209, v80, s[2:3]
	v_cndmask_b32_e64 v76, v209, v76, s[0:1]
	s_waitcnt vmcnt(0)
	ds_bpermute_b32 v156, v169, v156
	ds_bpermute_b32 v157, v169, v157
	ds_bpermute_b32 v158, v169, v158
	ds_bpermute_b32 v159, v169, v159
	ds_bpermute_b32 v160, v169, v160
	ds_bpermute_b32 v161, v169, v161
	ds_bpermute_b32 v162, v169, v162
	ds_bpermute_b32 v163, v169, v163
	ds_bpermute_b32 v164, v169, v164
	ds_bpermute_b32 v165, v169, v165
	ds_bpermute_b32 v166, v169, v166
	ds_bpermute_b32 v167, v169, v167
	ds_bpermute_b32 v190, v169, v190
	ds_bpermute_b32 v191, v169, v191
	ds_bpermute_b32 v192, v169, v192
	ds_bpermute_b32 v193, v169, v193
	s_waitcnt lgkmcnt(0)
	v_mfma_f32_16x16x32_bf16 v[60:63], v[60:63], v[156:159], v[194:197]
	v_mul_f32_e32 v80, 0x3e000000, v81
	v_cndmask_b32_e64 v200, v209, v88, s[16:17]
	v_mul_f32_e32 v88, 0x3e000000, v91
	s_waitcnt vmcnt(2)
	v_mfma_f32_16x16x32_bf16 v[64:67], v[64:67], v[160:163], v[60:63]
	v_cndmask_b32_e64 v91, v209, v84, s[14:15]
	v_mul_f32_e32 v84, 0x3e000000, v86
	v_cndmask_b32_e64 v86, v209, v80, s[2:3]
	v_mul_f32_e32 v80, 0x3e000000, v82
	v_mul_f32_e32 v60, 0x3e000000, v77
	s_nop 2
	v_mul_f32_e32 v64, 0x3e000000, v64
	v_cndmask_b32_e64 v81, v209, v64, s[42:43]
	v_mul_f32_e32 v64, 0x3e000000, v65
	v_max_f32_e32 v65, v76, v85
	v_max3_f32 v65, v65, v90, v94
	v_max3_f32 v65, v65, v98, v102
	v_max3_f32 v65, v65, v106, v110
	v_max3_f32 v65, v65, v114, v144
	v_max3_f32 v65, v65, v123, v127
	v_max3_f32 v65, v65, v131, v135
	v_cndmask_b32_e64 v156, v209, v64, s[42:43]
	v_mul_f32_e32 v64, 0x3e000000, v66
	v_max3_f32 v65, v65, v198, v81
	v_mov_b32_e32 v66, v145
	v_cndmask_b32_e64 v204, v209, v80, s[2:3]
	v_mul_f32_e32 v80, 0x3e000000, v83
	v_mov_b32_dpp v66, v65 row_ror:8 row_mask:0xf bank_mask:0xf
	v_max_f32_e32 v66, v66, v66
	v_max_f32_e32 v65, v65, v66
	v_mov_b32_e32 v66, v145
	v_cndmask_b32_e64 v83, v209, v60, s[0:1]
	v_mul_f32_e32 v77, 0x3e000000, v78
	v_mov_b32_dpp v66, v65 row_ror:4 row_mask:0xf bank_mask:0xf
	v_max_f32_e32 v66, v66, v66
	v_max_f32_e32 v65, v65, v66
	v_mov_b32_e32 v66, v145
	v_cndmask_b32_e64 v105, v209, v104, s[24:25]
	v_mul_f32_e32 v104, 0x3e000000, v107
	v_mov_b32_dpp v66, v65 row_ror:2 row_mask:0xf bank_mask:0xf
	v_max_f32_e32 v66, v66, v66
	v_max_f32_e32 v65, v65, v66
	v_mov_b32_e32 v66, v145
	v_cndmask_b32_e64 v107, v209, v77, s[0:1]
	v_cndmask_b32_e64 v201, v209, v84, s[14:15]
	v_mov_b32_dpp v66, v65 row_ror:1 row_mask:0xf bank_mask:0xf
	v_max_f32_e32 v66, v66, v66
	v_max_f32_e32 v65, v65, v66
	v_mov_b32_e32 v66, v145
	v_readfirstlane_b32 s85, v65
	v_max_f32_e32 v65, v83, v86
	v_max3_f32 v65, v65, v91, v89
	v_max3_f32 v65, v65, v93, v97
	v_max3_f32 v65, v65, v101, v111
	v_max3_f32 v65, v65, v115, v154
	v_max3_f32 v65, v65, v122, v126
	v_max3_f32 v65, v65, v130, v134
	v_max3_f32 v65, v65, v155, v156
	v_cndmask_b32_e64 v119, v209, v96, s[20:21]
	v_cndmask_b32_e64 v199, v209, v92, s[18:19]
	v_mov_b32_dpp v66, v65 row_ror:8 row_mask:0xf bank_mask:0xf
	v_max_f32_e32 v66, v66, v66
	v_max_f32_e32 v65, v65, v66
	v_mov_b32_e32 v66, v145
	v_cndmask_b32_e64 v118, v209, v100, s[22:23]
	v_cndmask_b32_e64 v157, v209, v64, s[42:43]
	v_mov_b32_dpp v66, v65 row_ror:4 row_mask:0xf bank_mask:0xf
	v_max_f32_e32 v66, v66, v66
	v_max_f32_e32 v65, v65, v66
	v_mov_b32_e32 v66, v145
	s_waitcnt vmcnt(1)
	v_mfma_f32_16x16x32_bf16 v[60:63], v[68:71], v[164:167], v[194:197]
	v_mul_f32_e32 v68, 0x3e000000, v79
	v_mov_b32_dpp v66, v65 row_ror:2 row_mask:0xf bank_mask:0xf
	v_max_f32_e32 v66, v66, v66
	v_max_f32_e32 v65, v65, v66
	v_mov_b32_e32 v66, v145
	v_mul_f32_e32 v84, 0x3e000000, v87
	v_cndmask_b32_e64 v80, v209, v80, s[2:3]
	v_mov_b32_dpp v66, v65 row_ror:1 row_mask:0xf bank_mask:0xf
	v_max_f32_e32 v66, v66, v66
	v_max_f32_e32 v65, v65, v66
	v_mov_b32_e32 v66, v145
	v_readfirstlane_b32 s86, v65
	v_max_f32_e32 v65, v107, v204
	v_max3_f32 v65, v65, v201, v200
	v_max3_f32 v65, v65, v199, v119
	v_max3_f32 v65, v65, v118, v105
	v_max3_f32 v65, v65, v109, v113
	v_max3_f32 v65, v65, v117, v121
	v_max3_f32 v65, v65, v125, v129
	v_max3_f32 v65, v65, v133, v157
	v_cndmask_b32_e64 v69, v209, v68, s[0:1]
	v_mul_f32_e32 v96, 0x3e000000, v99
	v_mov_b32_dpp v66, v65 row_ror:8 row_mask:0xf bank_mask:0xf
	v_max_f32_e32 v66, v66, v66
	v_max_f32_e32 v65, v65, v66
	v_mov_b32_e32 v66, v145
	v_mul_f32_e32 v92, 0x3e000000, v95
	v_cndmask_b32_e64 v88, v209, v88, s[16:17]
	v_mov_b32_dpp v66, v65 row_ror:4 row_mask:0xf bank_mask:0xf
	v_max_f32_e32 v66, v66, v66
	v_max_f32_e32 v65, v65, v66
	v_mov_b32_e32 v66, v145
	v_cndmask_b32_e64 v84, v209, v84, s[14:15]
	v_mul_f32_e32 v100, 0x3e000000, v103
	v_mov_b32_dpp v66, v65 row_ror:2 row_mask:0xf bank_mask:0xf
	v_max_f32_e32 v66, v66, v66
	v_max_f32_e32 v65, v65, v66
	v_mov_b32_e32 v66, v145
	v_cndmask_b32_e64 v96, v209, v96, s[20:21]
	v_cndmask_b32_e64 v92, v209, v92, s[18:19]
	v_mov_b32_dpp v66, v65 row_ror:1 row_mask:0xf bank_mask:0xf
	v_max_f32_e32 v66, v66, v66
	v_max_f32_e32 v65, v65, v66
	v_cndmask_b32_e64 v104, v209, v104, s[24:25]
	v_readfirstlane_b32 s45, v65
	v_max_f32_e32 v65, v69, v80
	v_max3_f32 v65, v65, v84, v88
	v_cndmask_b32_e64 v100, v209, v100, s[22:23]
	v_max3_f32 v65, v65, v92, v96
	v_cndmask_b32_e64 v112, v209, v112, s[28:29]
	v_cndmask_b32_e64 v108, v209, v108, s[26:27]
	v_max3_f32 v65, v65, v100, v104
	v_cndmask_b32_e64 v120, v209, v120, s[34:35]
	v_cndmask_b32_e64 v116, v209, v116, s[30:31]
	v_max3_f32 v65, v65, v108, v112
	v_cndmask_b32_e64 v128, v209, v128, s[38:39]
	v_cndmask_b32_e64 v124, v209, v124, s[36:37]
	v_mul_f32_e32 v64, 0x3e000000, v67
	v_max3_f32 v65, v65, v116, v120
	v_cndmask_b32_e64 v132, v209, v132, s[40:41]
	v_cndmask_b32_e64 v64, v209, v64, s[42:43]
	v_max3_f32 v65, v65, v124, v128
	v_max3_f32 v65, v65, v132, v64
	v_mov_b32_e32 v66, v145
	v_cmp_lt_f32_e32 vcc, s83, v76
	v_subrev_f32_e32 v70, s85, v94
	v_mov_b32_dpp v66, v65 row_ror:8 row_mask:0xf bank_mask:0xf
	v_max_f32_e32 v66, v66, v66
	v_max_f32_e32 v65, v65, v66
	v_mov_b32_e32 v66, v145
	v_mul_f32_e32 v70, 0x3fb8aa3b, v70
	v_exp_f32_e32 v70, v70
	v_mov_b32_dpp v66, v65 row_ror:4 row_mask:0xf bank_mask:0xf
	v_max_f32_e32 v66, v66, v66
	v_max_f32_e32 v65, v65, v66
	v_mov_b32_e32 v66, v145
	s_waitcnt vmcnt(0)
	v_mfma_f32_16x16x32_bf16 v[60:63], v[72:75], v[190:193], v[60:63]
	v_subrev_f32_e32 v72, s85, v102
	v_mov_b32_dpp v66, v65 row_ror:2 row_mask:0xf bank_mask:0xf
	v_max_f32_e32 v66, v66, v66
	v_max_f32_e32 v65, v65, v66
	v_mov_b32_e32 v66, v145
	v_mul_f32_e32 v72, 0x3fb8aa3b, v72
	v_exp_f32_e32 v72, v72
	v_mov_b32_dpp v66, v65 row_ror:1 row_mask:0xf bank_mask:0xf
	v_max_f32_e32 v66, v66, v66
	v_max_f32_e32 v65, v65, v66
	v_subrev_f32_e32 v66, s85, v85
	v_readfirstlane_b32 s44, v65
	v_subrev_f32_e32 v65, s85, v76
	v_mul_f32_e32 v65, 0x3fb8aa3b, v65
	v_exp_f32_e32 v65, v65
	v_mul_f32_e32 v66, 0x3fb8aa3b, v66
	v_exp_f32_e32 v67, v66
	v_subrev_f32_e32 v74, s85, v110
	v_cndmask_b32_e32 v66, 0, v65, vcc
	v_cmp_lt_f32_e32 vcc, s83, v85
	v_add_f32_e32 v68, 0, v66
	v_mul_f32_e32 v74, 0x3fb8aa3b, v74
	v_cndmask_b32_e32 v65, 0, v67, vcc
	v_add_f32_e32 v67, v65, v68
	v_subrev_f32_e32 v68, s85, v90
	v_mul_f32_e32 v68, 0x3fb8aa3b, v68
	v_exp_f32_e32 v68, v68
	v_cmp_lt_f32_e32 vcc, s83, v90
	v_exp_f32_e32 v74, v74
	v_subrev_f32_e32 v76, s85, v144
	v_cndmask_b32_e32 v68, 0, v68, vcc
	v_cmp_lt_f32_e32 vcc, s83, v94
	v_add_f32_e32 v71, v68, v67
	v_mul_f32_e32 v76, 0x3fb8aa3b, v76
	v_cndmask_b32_e32 v67, 0, v70, vcc
	v_add_f32_e32 v70, v67, v71
	v_subrev_f32_e32 v71, s85, v98
	v_mul_f32_e32 v71, 0x3fb8aa3b, v71
	v_exp_f32_e32 v71, v71
	v_cmp_lt_f32_e32 vcc, s83, v98
	v_exp_f32_e32 v76, v76
	v_subrev_f32_e32 v78, s85, v127
	v_cndmask_b32_e32 v71, 0, v71, vcc
	v_cmp_lt_f32_e32 vcc, s83, v102
	v_add_f32_e32 v73, v71, v70
	v_mul_f32_e32 v78, 0x3fb8aa3b, v78
	v_cndmask_b32_e32 v70, 0, v72, vcc
	v_add_f32_e32 v72, v70, v73
	v_subrev_f32_e32 v73, s85, v106
	v_mul_f32_e32 v73, 0x3fb8aa3b, v73
	v_exp_f32_e32 v73, v73
	v_cmp_lt_f32_e32 vcc, s83, v106
	v_exp_f32_e32 v78, v78
	v_subrev_f32_e32 v82, s85, v135
	v_cndmask_b32_e32 v73, 0, v73, vcc
	v_cmp_lt_f32_e32 vcc, s83, v110
	v_add_f32_e32 v75, v73, v72
	v_mul_f32_e32 v82, 0x3fb8aa3b, v82
	v_cndmask_b32_e32 v72, 0, v74, vcc
	v_add_f32_e32 v74, v72, v75
	v_subrev_f32_e32 v75, s85, v114
	v_mul_f32_e32 v75, 0x3fb8aa3b, v75
	v_exp_f32_e32 v75, v75
	v_cmp_lt_f32_e32 vcc, s83, v114
	v_exp_f32_e32 v82, v82
	v_subrev_f32_e32 v87, s85, v81
	v_cndmask_b32_e32 v75, 0, v75, vcc
	v_cmp_lt_f32_e32 vcc, s83, v144
	v_add_f32_e32 v77, v75, v74
	v_mul_f32_e32 v87, 0x3fb8aa3b, v87
	v_cndmask_b32_e32 v74, 0, v76, vcc
	v_add_f32_e32 v76, v74, v77
	v_subrev_f32_e32 v77, s85, v123
	v_mul_f32_e32 v77, 0x3fb8aa3b, v77
	v_exp_f32_e32 v77, v77
	v_cmp_lt_f32_e32 vcc, s83, v123
	v_exp_f32_e32 v87, v87
	v_subrev_f32_e32 v94, s86, v111
	v_cndmask_b32_e32 v77, 0, v77, vcc
	v_cmp_lt_f32_e32 vcc, s83, v127
	v_add_f32_e32 v79, v77, v76
	v_mul_f32_e32 v94, 0x3fb8aa3b, v94
	v_cndmask_b32_e32 v76, 0, v78, vcc
	v_add_f32_e32 v78, v76, v79
	v_subrev_f32_e32 v79, s85, v131
	v_mul_f32_e32 v79, 0x3fb8aa3b, v79
	v_exp_f32_e32 v79, v79
	v_cmp_lt_f32_e32 vcc, s83, v131
	v_exp_f32_e32 v94, v94
	v_subrev_f32_e32 v99, s86, v126
	v_cndmask_b32_e32 v79, 0, v79, vcc
	v_cmp_lt_f32_e32 vcc, s83, v135
	v_add_f32_e32 v85, v79, v78
	v_mul_f32_e32 v99, 0x3fb8aa3b, v99
	v_cndmask_b32_e32 v78, 0, v82, vcc
	v_subrev_f32_e32 v82, s85, v198
	v_mul_f32_e32 v82, 0x3fb8aa3b, v82
	v_exp_f32_e32 v82, v82
	v_cmp_lt_f32_e32 vcc, s83, v198
	v_add_f32_e32 v85, v78, v85
	v_exp_f32_e32 v99, v99
	v_cndmask_b32_e32 v82, 0, v82, vcc
	v_cmp_lt_f32_e32 vcc, s83, v81
	v_add_f32_e32 v85, v82, v85
	v_subrev_f32_e32 v102, s86, v134
	v_cndmask_b32_e32 v81, 0, v87, vcc
	v_add_f32_e32 v85, v81, v85
	v_subrev_f32_e32 v87, s86, v86
	v_mul_f32_e32 v87, 0x3fb8aa3b, v87
	v_add_f32_dpp v85, v85, v85 row_ror:8 row_mask:0xf bank_mask:0xf bound_ctrl:1
	v_exp_f32_e32 v87, v87
	v_cmp_lt_f32_e32 vcc, s83, v83
	v_add_f32_dpp v85, v85, v85 row_ror:4 row_mask:0xf bank_mask:0xf bound_ctrl:1
	v_mul_f32_e32 v102, 0x3fb8aa3b, v102
	v_exp_f32_e32 v102, v102
	v_add_f32_dpp v85, v85, v85 row_ror:2 row_mask:0xf bank_mask:0xf bound_ctrl:1
	v_subrev_f32_e32 v106, s86, v156
	v_mul_f32_e32 v106, 0x3fb8aa3b, v106
	v_add_f32_dpp v85, v85, v85 row_ror:1 row_mask:0xf bank_mask:0xf bound_ctrl:1
	v_exp_f32_e32 v106, v106
	v_readfirstlane_b32 s85, v85
	v_subrev_f32_e32 v85, s86, v83
	v_mul_f32_e32 v85, 0x3fb8aa3b, v85
	v_exp_f32_e32 v85, v85
	v_subrev_f32_e32 v114, s45, v200
	v_mul_f32_e32 v114, 0x3fb8aa3b, v114
	v_exp_f32_e32 v114, v114
	v_cndmask_b32_e32 v85, 0, v85, vcc
	v_cmp_lt_f32_e32 vcc, s83, v86
	v_add_f32_e32 v90, 0, v85
	s_nop 0
	v_cndmask_b32_e32 v83, 0, v87, vcc
	v_subrev_f32_e32 v87, s86, v91
	v_add_f32_e32 v86, v83, v90
	v_mul_f32_e32 v87, 0x3fb8aa3b, v87
	v_subrev_f32_e32 v90, s86, v89
	v_exp_f32_e32 v87, v87
	v_mul_f32_e32 v90, 0x3fb8aa3b, v90
	v_exp_f32_e32 v90, v90
	v_cmp_lt_f32_e32 vcc, s83, v91
	s_nop 1
	v_cndmask_b32_e32 v87, 0, v87, vcc
	v_cmp_lt_f32_e32 vcc, s83, v89
	v_add_f32_e32 v91, v87, v86
	s_nop 0
	v_cndmask_b32_e32 v86, 0, v90, vcc
	v_subrev_f32_e32 v90, s86, v93
	v_add_f32_e32 v89, v86, v91
	v_mul_f32_e32 v90, 0x3fb8aa3b, v90
	v_subrev_f32_e32 v91, s86, v97
	v_exp_f32_e32 v90, v90
	v_mul_f32_e32 v91, 0x3fb8aa3b, v91
	v_exp_f32_e32 v91, v91
	v_cmp_lt_f32_e32 vcc, s83, v93
	s_nop 1
	v_cndmask_b32_e32 v90, 0, v90, vcc
	v_cmp_lt_f32_e32 vcc, s83, v97
	v_add_f32_e32 v93, v90, v89
	v_subrev_f32_e32 v97, s86, v154
	v_cndmask_b32_e32 v89, 0, v91, vcc
	v_add_f32_e32 v91, v89, v93
	v_subrev_f32_e32 v93, s86, v101
	v_mul_f32_e32 v93, 0x3fb8aa3b, v93
	v_exp_f32_e32 v93, v93
	v_cmp_lt_f32_e32 vcc, s83, v101
	v_mul_f32_e32 v97, 0x3fb8aa3b, v97
	v_exp_f32_e32 v97, v97
	v_cndmask_b32_e32 v93, 0, v93, vcc
	v_cmp_lt_f32_e32 vcc, s83, v111
	v_add_f32_e32 v95, v93, v91
	s_nop 0
	v_cndmask_b32_e32 v91, 0, v94, vcc
	v_add_f32_e32 v94, v91, v95
	v_subrev_f32_e32 v95, s86, v115
	v_mul_f32_e32 v95, 0x3fb8aa3b, v95
	v_exp_f32_e32 v95, v95
	v_cmp_lt_f32_e32 vcc, s83, v115
	s_nop 1
	v_cndmask_b32_e32 v95, 0, v95, vcc
	v_cmp_lt_f32_e32 vcc, s83, v154
	v_add_f32_e32 v98, v95, v94
	s_nop 0
	v_cndmask_b32_e32 v94, 0, v97, vcc
	v_add_f32_e32 v97, v94, v98
	v_subrev_f32_e32 v98, s86, v122
	v_mul_f32_e32 v98, 0x3fb8aa3b, v98
	v_exp_f32_e32 v98, v98
	v_cmp_lt_f32_e32 vcc, s83, v122
	v_subrev_f32_e32 v122, s45, v119
	v_mul_f32_e32 v122, 0x3fb8aa3b, v122
	v_cndmask_b32_e32 v98, 0, v98, vcc
	v_cmp_lt_f32_e32 vcc, s83, v126
	v_add_f32_e32 v101, v98, v97
	v_exp_f32_e32 v122, v122
	v_cndmask_b32_e32 v97, 0, v99, vcc
	v_add_f32_e32 v99, v97, v101
	v_subrev_f32_e32 v101, s86, v130
	v_mul_f32_e32 v101, 0x3fb8aa3b, v101
	v_exp_f32_e32 v101, v101
	v_cmp_lt_f32_e32 vcc, s83, v130
	v_subrev_f32_e32 v126, s45, v157
	v_mul_f32_e32 v126, 0x3fb8aa3b, v126
	v_cndmask_b32_e32 v101, 0, v101, vcc
	v_cmp_lt_f32_e32 vcc, s83, v134
	v_add_f32_e32 v103, v101, v99
	v_exp_f32_e32 v126, v126
	v_cndmask_b32_e32 v99, 0, v102, vcc
	v_add_f32_e32 v102, v99, v103
	v_subrev_f32_e32 v103, s86, v155
	v_mul_f32_e32 v103, 0x3fb8aa3b, v103
	v_exp_f32_e32 v103, v103
	v_cmp_lt_f32_e32 vcc, s83, v155
	s_nop 1
	v_cndmask_b32_e32 v103, 0, v103, vcc
	v_cmp_lt_f32_e32 vcc, s83, v156
	v_add_f32_e32 v110, v103, v102
	s_nop 0
	v_cndmask_b32_e32 v102, 0, v106, vcc
	v_add_f32_e32 v106, v102, v110
	v_subrev_f32_e32 v110, s45, v204
	v_mul_f32_e32 v110, 0x3fb8aa3b, v110
	v_add_f32_dpp v106, v106, v106 row_ror:8 row_mask:0xf bank_mask:0xf bound_ctrl:1
	v_exp_f32_e32 v110, v110
	v_cmp_lt_f32_e32 vcc, s83, v107
	v_add_f32_dpp v106, v106, v106 row_ror:4 row_mask:0xf bank_mask:0xf bound_ctrl:1
	s_nop 1
	v_add_f32_dpp v106, v106, v106 row_ror:2 row_mask:0xf bank_mask:0xf bound_ctrl:1
	s_nop 1
	v_add_f32_dpp v106, v106, v106 row_ror:1 row_mask:0xf bank_mask:0xf bound_ctrl:1
	s_nop 0
	v_readfirstlane_b32 s86, v106
	v_subrev_f32_e32 v106, s45, v107
	v_mul_f32_e32 v106, 0x3fb8aa3b, v106
	v_exp_f32_e32 v106, v106
	s_nop 0
	v_cndmask_b32_e32 v107, 0, v106, vcc
	v_cmp_lt_f32_e32 vcc, s83, v204
	v_add_f32_e32 v111, 0, v107
	s_nop 0
	v_cndmask_b32_e32 v106, 0, v110, vcc
	v_add_f32_e32 v110, v106, v111
	v_subrev_f32_e32 v111, s45, v201
	v_mul_f32_e32 v111, 0x3fb8aa3b, v111
	v_exp_f32_e32 v111, v111
	v_cmp_lt_f32_e32 vcc, s83, v201
	s_nop 1
	v_cndmask_b32_e32 v111, 0, v111, vcc
	v_cmp_lt_f32_e32 vcc, s83, v200
	v_add_f32_e32 v115, v111, v110
	s_nop 0
	v_cndmask_b32_e32 v110, 0, v114, vcc
	v_add_f32_e32 v114, v110, v115
	v_subrev_f32_e32 v115, s45, v199
	v_mul_f32_e32 v115, 0x3fb8aa3b, v115
	v_exp_f32_e32 v115, v115
	v_cmp_lt_f32_e32 vcc, s83, v199
	s_nop 1
	v_cndmask_b32_e32 v115, 0, v115, vcc
	v_cmp_lt_f32_e32 vcc, s83, v119
	v_add_f32_e32 v123, v115, v114
	s_nop 0
	v_cndmask_b32_e32 v114, 0, v122, vcc
	v_subrev_f32_e32 v122, s45, v118
	v_add_f32_e32 v119, v114, v123
	v_mul_f32_e32 v122, 0x3fb8aa3b, v122
	v_subrev_f32_e32 v123, s45, v105
	v_exp_f32_e32 v122, v122
	v_mul_f32_e32 v123, 0x3fb8aa3b, v123
	v_exp_f32_e32 v123, v123
	v_cmp_lt_f32_e32 vcc, s83, v118
	s_nop 1
	v_cndmask_b32_e32 v118, 0, v122, vcc
	v_cmp_lt_f32_e32 vcc, s83, v105
	v_add_f32_e32 v119, v118, v119
	s_nop 0
	v_cndmask_b32_e32 v105, 0, v123, vcc
	v_add_f32_e32 v122, v105, v119
	v_subrev_f32_e32 v119, s45, v109
	v_mul_f32_e32 v119, 0x3fb8aa3b, v119
	v_subrev_f32_e32 v123, s45, v113
	v_exp_f32_e32 v119, v119
	v_mul_f32_e32 v123, 0x3fb8aa3b, v123
	v_exp_f32_e32 v123, v123
	v_cmp_lt_f32_e32 vcc, s83, v109
	s_nop 1
	v_cndmask_b32_e32 v119, 0, v119, vcc
	v_cmp_lt_f32_e32 vcc, s83, v113
	v_add_f32_e32 v122, v119, v122
	s_nop 0
	v_cndmask_b32_e32 v109, 0, v123, vcc
	v_add_f32_e32 v113, v109, v122
	v_subrev_f32_e32 v122, s45, v117
	v_mul_f32_e32 v122, 0x3fb8aa3b, v122
	v_subrev_f32_e32 v123, s45, v121
	v_exp_f32_e32 v122, v122
	v_mul_f32_e32 v123, 0x3fb8aa3b, v123
	v_exp_f32_e32 v123, v123
	v_cmp_lt_f32_e32 vcc, s83, v117
	s_nop 1
	v_cndmask_b32_e32 v117, 0, v122, vcc
	v_cmp_lt_f32_e32 vcc, s83, v121
	v_add_f32_e32 v122, v117, v113
	s_nop 0
	v_cndmask_b32_e32 v113, 0, v123, vcc
	v_add_f32_e32 v121, v113, v122
	v_subrev_f32_e32 v122, s45, v125
	v_mul_f32_e32 v122, 0x3fb8aa3b, v122
	v_subrev_f32_e32 v123, s45, v129
	v_exp_f32_e32 v122, v122
	v_mul_f32_e32 v123, 0x3fb8aa3b, v123
	v_exp_f32_e32 v123, v123
	v_cmp_lt_f32_e32 vcc, s83, v125
	s_nop 1
	v_cndmask_b32_e32 v122, 0, v122, vcc
	v_cmp_lt_f32_e32 vcc, s83, v129
	v_add_f32_e32 v125, v122, v121
	s_nop 0
	v_cndmask_b32_e32 v121, 0, v123, vcc
	v_add_f32_e32 v123, v121, v125
	v_subrev_f32_e32 v125, s45, v133
	v_mul_f32_e32 v125, 0x3fb8aa3b, v125
	v_exp_f32_e32 v125, v125
	v_cmp_lt_f32_e32 vcc, s83, v133
	s_nop 1
	v_cndmask_b32_e32 v125, 0, v125, vcc
	v_cmp_lt_f32_e32 vcc, s83, v157
	v_add_f32_e32 v127, v125, v123
	s_nop 0
	v_cndmask_b32_e32 v123, 0, v126, vcc
	v_add_f32_e32 v126, v123, v127
	v_subrev_f32_e32 v127, s44, v80
	v_mul_f32_e32 v127, 0x3fb8aa3b, v127
	v_add_f32_dpp v126, v126, v126 row_ror:8 row_mask:0xf bank_mask:0xf bound_ctrl:1
	v_exp_f32_e32 v127, v127
	v_cmp_lt_f32_e32 vcc, s83, v69
	v_add_f32_dpp v126, v126, v126 row_ror:4 row_mask:0xf bank_mask:0xf bound_ctrl:1
	s_nop 1
	v_add_f32_dpp v126, v126, v126 row_ror:2 row_mask:0xf bank_mask:0xf bound_ctrl:1
	s_nop 1
	v_add_f32_dpp v126, v126, v126 row_ror:1 row_mask:0xf bank_mask:0xf bound_ctrl:1
	s_nop 0
	v_readfirstlane_b32 s87, v126
	v_subrev_f32_e32 v126, s44, v69
	v_mul_f32_e32 v126, 0x3fb8aa3b, v126
	v_exp_f32_e32 v126, v126
	s_nop 0
	v_cndmask_b32_e32 v126, 0, v126, vcc
	v_cmp_lt_f32_e32 vcc, s83, v80
	v_add_f32_e32 v129, 0, v126
	s_nop 0
	v_cndmask_b32_e32 v69, 0, v127, vcc
	v_subrev_f32_e32 v127, s44, v84
	v_add_f32_e32 v80, v69, v129
	v_mul_f32_e32 v127, 0x3fb8aa3b, v127
	v_subrev_f32_e32 v129, s44, v88
	v_exp_f32_e32 v127, v127
	v_mul_f32_e32 v129, 0x3fb8aa3b, v129
	v_exp_f32_e32 v129, v129
	v_cmp_lt_f32_e32 vcc, s83, v84
	s_nop 1
	v_cndmask_b32_e32 v84, 0, v127, vcc
	v_cmp_lt_f32_e32 vcc, s83, v88
	v_add_f32_e32 v127, v84, v80
	s_nop 0
	v_cndmask_b32_e32 v80, 0, v129, vcc
	v_add_f32_e32 v88, v80, v127
	v_subrev_f32_e32 v127, s44, v92
	v_mul_f32_e32 v127, 0x3fb8aa3b, v127
	v_subrev_f32_e32 v129, s44, v96
	v_exp_f32_e32 v127, v127
	v_mul_f32_e32 v129, 0x3fb8aa3b, v129
	v_exp_f32_e32 v129, v129
	v_cmp_lt_f32_e32 vcc, s83, v92
	s_nop 1
	v_cndmask_b32_e32 v92, 0, v127, vcc
	v_cmp_lt_f32_e32 vcc, s83, v96
	v_add_f32_e32 v127, v92, v88
	s_nop 0
	v_cndmask_b32_e32 v88, 0, v129, vcc
	v_add_f32_e32 v96, v88, v127
	v_subrev_f32_e32 v127, s44, v100
	v_mul_f32_e32 v127, 0x3fb8aa3b, v127
	v_subrev_f32_e32 v129, s44, v104
	v_exp_f32_e32 v127, v127
	v_mul_f32_e32 v129, 0x3fb8aa3b, v129
	v_exp_f32_e32 v129, v129
	v_cmp_lt_f32_e32 vcc, s83, v100
	s_nop 1
	v_cndmask_b32_e32 v100, 0, v127, vcc
	v_cmp_lt_f32_e32 vcc, s83, v104
	v_add_f32_e32 v127, v100, v96
	s_nop 0
	v_cndmask_b32_e32 v96, 0, v129, vcc
	v_add_f32_e32 v104, v96, v127
	v_subrev_f32_e32 v127, s44, v108
	v_mul_f32_e32 v127, 0x3fb8aa3b, v127
	v_subrev_f32_e32 v129, s44, v112
	v_exp_f32_e32 v127, v127
	v_mul_f32_e32 v129, 0x3fb8aa3b, v129
	v_exp_f32_e32 v129, v129
	v_cmp_lt_f32_e32 vcc, s83, v108
	s_nop 1
	v_cndmask_b32_e32 v108, 0, v127, vcc
	v_cmp_lt_f32_e32 vcc, s83, v112
	v_add_f32_e32 v127, v108, v104
	s_nop 0
	v_cndmask_b32_e32 v104, 0, v129, vcc
	v_add_f32_e32 v112, v104, v127
	v_subrev_f32_e32 v127, s44, v116
	v_mul_f32_e32 v127, 0x3fb8aa3b, v127
	v_subrev_f32_e32 v129, s44, v120
	v_exp_f32_e32 v127, v127
	v_mul_f32_e32 v129, 0x3fb8aa3b, v129
	v_exp_f32_e32 v129, v129
	v_cmp_lt_f32_e32 vcc, s83, v116
	s_nop 1
	v_cndmask_b32_e32 v116, 0, v127, vcc
	v_cmp_lt_f32_e32 vcc, s83, v120
	v_add_f32_e32 v127, v116, v112
	s_nop 0
	v_cndmask_b32_e32 v112, 0, v129, vcc
	v_add_f32_e32 v120, v112, v127
	v_subrev_f32_e32 v127, s44, v124
	v_mul_f32_e32 v127, 0x3fb8aa3b, v127
	v_subrev_f32_e32 v129, s44, v128
	v_exp_f32_e32 v127, v127
	v_mul_f32_e32 v129, 0x3fb8aa3b, v129
	v_exp_f32_e32 v129, v129
	v_cmp_lt_f32_e32 vcc, s83, v124
	s_nop 1
	v_cndmask_b32_e32 v124, 0, v127, vcc
	v_cmp_lt_f32_e32 vcc, s83, v128
	v_subrev_f32_e32 v128, s44, v132
	v_add_f32_e32 v127, v124, v120
	v_cndmask_b32_e32 v120, 0, v129, vcc
	v_mul_f32_e32 v128, 0x3fb8aa3b, v128
	v_subrev_f32_e32 v129, s44, v64
	v_exp_f32_e32 v128, v128
	v_mul_f32_e32 v129, 0x3fb8aa3b, v129
	v_exp_f32_e32 v129, v129
	v_cmp_lt_f32_e32 vcc, s83, v132
	v_add_f32_e32 v127, v120, v127
	s_nop 0
	v_cndmask_b32_e32 v128, 0, v128, vcc
	v_cmp_lt_f32_e32 vcc, s83, v64
	v_add_f32_e32 v130, v128, v127
	s_nop 0
	v_cndmask_b32_e32 v127, 0, v129, vcc
	v_add_f32_e32 v64, v127, v130
	s_nop 1
	v_add_f32_dpp v64, v64, v64 row_ror:8 row_mask:0xf bank_mask:0xf bound_ctrl:1
	s_nop 1
	v_add_f32_dpp v64, v64, v64 row_ror:4 row_mask:0xf bank_mask:0xf bound_ctrl:1
	s_nop 1
	v_add_f32_dpp v64, v64, v64 row_ror:2 row_mask:0xf bank_mask:0xf bound_ctrl:1
	s_nop 1
	v_add_f32_dpp v64, v64, v64 row_ror:1 row_mask:0xf bank_mask:0xf bound_ctrl:1
	s_nop 0
	v_readfirstlane_b32 s88, v64
	v_add_u32_e32 v64, 0x800, v186
	s_and_saveexec_b64 s[44:45], s[6:7]
	s_cbranch_execz .LBB0_1532
	v_cvt_pk_bf16_f32 v130, v66, v85
	v_cvt_pk_bf16_f32 v133, v106, v69
	v_cvt_pk_bf16_f32 v68, v68, v87
	v_cvt_pk_bf16_f32 v69, v111, v84
	v_cvt_pk_bf16_f32 v66, v67, v86
	v_cvt_pk_bf16_f32 v67, v110, v80
	ds_write2_b64 v186, v[68:69], v[66:67] offset0:64 offset1:96
	v_cvt_pk_bf16_f32 v66, v71, v90
	v_cvt_pk_bf16_f32 v67, v115, v92
	v_cvt_pk_bf16_f32 v68, v70, v89
	v_cvt_pk_bf16_f32 v69, v114, v88
	ds_write2_b64 v186, v[66:67], v[68:69] offset0:128 offset1:160
	v_cvt_pk_bf16_f32 v66, v73, v93
	v_cvt_pk_bf16_f32 v67, v118, v100
	v_cvt_pk_bf16_f32 v68, v72, v91
	v_cvt_pk_bf16_f32 v69, v105, v96
	ds_write2_b64 v186, v[66:67], v[68:69] offset0:192 offset1:224
	v_cvt_pk_bf16_f32 v66, v75, v95
	v_cvt_pk_bf16_f32 v67, v119, v108
	v_cvt_pk_bf16_f32 v68, v74, v94
	v_cvt_pk_bf16_f32 v69, v109, v104
	ds_write2_b64 v64, v[66:67], v[68:69] offset1:32
	v_cvt_pk_bf16_f32 v66, v77, v98
	v_cvt_pk_bf16_f32 v67, v117, v116
	v_cvt_pk_bf16_f32 v68, v76, v97
	v_cvt_pk_bf16_f32 v69, v113, v112
	ds_write2_b64 v64, v[66:67], v[68:69] offset0:64 offset1:96
	v_cvt_pk_bf16_f32 v66, v79, v101
	v_cvt_pk_bf16_f32 v67, v122, v124
	v_cvt_pk_bf16_f32 v68, v78, v99
	v_cvt_pk_bf16_f32 v69, v121, v120
	v_cvt_pk_bf16_f32 v131, v107, v126
	v_cvt_pk_bf16_f32 v132, v65, v83
	ds_write2_b64 v64, v[66:67], v[68:69] offset0:128 offset1:160
	v_cvt_pk_bf16_f32 v66, v82, v103
	v_cvt_pk_bf16_f32 v67, v125, v128
	v_cvt_pk_bf16_f32 v68, v81, v102
	v_cvt_pk_bf16_f32 v69, v123, v127
	ds_write2_b64 v186, v[130:131], v[132:133] offset1:32
	ds_write2_b64 v64, v[66:67], v[68:69] offset0:192 offset1:224
